# skinny sample-row GEMM of the two K=5632 down projections: all A fragments requested up front instead of one round trip per MFMA
# baseline (speedup 1.0000x reference)
.LBB0_676:
	v_add_co_u32_e32 v106, vcc, s1, v94
	s_nop 1
	v_addc_co_u32_e32 v107, vcc, 0, v95, vcc
	v_add_co_u32_e32 v108, vcc, s10, v94
	s_nop 1
	v_addc_co_u32_e32 v109, vcc, 0, v95, vcc
	v_add_co_u32_e32 v110, vcc, s11, v94
	s_nop 1
	v_addc_co_u32_e32 v111, vcc, 0, v95, vcc
	global_load_dwordx4 v[112:115], v[94:95], off offset:128
	global_load_dwordx4 v[116:119], v[106:107], off offset:128
	global_load_dwordx4 v[120:123], v[108:109], off offset:128
	global_load_dwordx4 v[124:127], v[110:111], off offset:128
	global_load_dwordx4 v[128:131], v[94:95], off offset:192
	global_load_dwordx4 v[132:135], v[106:107], off offset:192
	global_load_dwordx4 v[136:139], v[108:109], off offset:192
	global_load_dwordx4 v[140:143], v[110:111], off offset:192
	global_load_dwordx4 v[144:147], v[94:95], off offset:256
	global_load_dwordx4 v[148:151], v[106:107], off offset:256
	global_load_dwordx4 v[152:155], v[108:109], off offset:256
	global_load_dwordx4 v[156:159], v[110:111], off offset:256
	global_load_dwordx4 v[160:163], v[94:95], off offset:320
	global_load_dwordx4 v[164:167], v[106:107], off offset:320
	global_load_dwordx4 v[168:171], v[108:109], off offset:320
	global_load_dwordx4 v[172:175], v[110:111], off offset:320
	global_load_dwordx4 v[176:179], v[94:95], off offset:384
	global_load_dwordx4 v[180:183], v[106:107], off offset:384
	global_load_dwordx4 v[184:187], v[108:109], off offset:384
	global_load_dwordx4 v[188:191], v[110:111], off offset:384
	global_load_dwordx4 v[192:195], v[94:95], off offset:448
	global_load_dwordx4 v[196:199], v[106:107], off offset:448
	global_load_dwordx4 v[200:203], v[108:109], off offset:448
	global_load_dwordx4 v[204:207], v[110:111], off offset:448
	global_load_dwordx4 v[208:211], v[94:95], off offset:512
	global_load_dwordx4 v[212:215], v[106:107], off offset:512
	global_load_dwordx4 v[216:219], v[108:109], off offset:512
	global_load_dwordx4 v[220:223], v[110:111], off offset:512
	global_load_dwordx4 v[224:227], v[94:95], off offset:576
	global_load_dwordx4 v[228:231], v[106:107], off offset:576
	global_load_dwordx4 v[232:235], v[108:109], off offset:576
	global_load_dwordx4 v[236:239], v[110:111], off offset:576
	s_waitcnt vmcnt(32)
	v_mfma_f32_16x16x32_bf16 v[84:87], v[56:59], v[0:3], 0
	v_mfma_f32_16x16x32_bf16 v[76:79], v[44:47], v[0:3], 0
	v_mfma_f32_16x16x32_bf16 v[80:83], v[48:51], v[0:3], 0
	v_mfma_f32_16x16x32_bf16 v[88:91], v[68:71], v[0:3], 0
	v_mfma_f32_16x16x32_bf16 v[84:87], v[60:63], v[4:7], v[84:87]
	v_mfma_f32_16x16x32_bf16 v[76:79], v[52:55], v[4:7], v[76:79]
	v_mfma_f32_16x16x32_bf16 v[80:83], v[72:75], v[4:7], v[80:83]
	v_mfma_f32_16x16x32_bf16 v[88:91], v[64:67], v[4:7], v[88:91]
	global_load_dwordx4 v[56:59], v[94:95], off offset:640
	global_load_dwordx4 v[44:47], v[106:107], off offset:640
	global_load_dwordx4 v[48:51], v[108:109], off offset:640
	global_load_dwordx4 v[68:71], v[110:111], off offset:640
	s_waitcnt vmcnt(32)
	v_mfma_f32_16x16x32_bf16 v[84:87], v[112:115], v[8:11], v[84:87]
	v_mfma_f32_16x16x32_bf16 v[76:79], v[116:119], v[8:11], v[76:79]
	v_mfma_f32_16x16x32_bf16 v[80:83], v[120:123], v[8:11], v[80:83]
	v_mfma_f32_16x16x32_bf16 v[88:91], v[124:127], v[8:11], v[88:91]
	s_waitcnt vmcnt(28)
	v_mfma_f32_16x16x32_bf16 v[84:87], v[128:131], v[12:15], v[84:87]
	v_mfma_f32_16x16x32_bf16 v[76:79], v[132:135], v[12:15], v[76:79]
	v_mfma_f32_16x16x32_bf16 v[80:83], v[136:139], v[12:15], v[80:83]
	v_mfma_f32_16x16x32_bf16 v[88:91], v[140:143], v[12:15], v[88:91]
	s_waitcnt vmcnt(24)
	v_mfma_f32_16x16x32_bf16 v[84:87], v[144:147], v[16:19], v[84:87]
	v_mfma_f32_16x16x32_bf16 v[76:79], v[148:151], v[16:19], v[76:79]
	v_mfma_f32_16x16x32_bf16 v[80:83], v[152:155], v[16:19], v[80:83]
	v_mfma_f32_16x16x32_bf16 v[88:91], v[156:159], v[16:19], v[88:91]
	s_waitcnt vmcnt(20)
	v_mfma_f32_16x16x32_bf16 v[84:87], v[160:163], v[20:23], v[84:87]
	v_mfma_f32_16x16x32_bf16 v[76:79], v[164:167], v[20:23], v[76:79]
	v_mfma_f32_16x16x32_bf16 v[80:83], v[168:171], v[20:23], v[80:83]
	v_mfma_f32_16x16x32_bf16 v[88:91], v[172:175], v[20:23], v[88:91]
	s_waitcnt vmcnt(16)
	v_mfma_f32_16x16x32_bf16 v[84:87], v[176:179], v[24:27], v[84:87]
	v_mfma_f32_16x16x32_bf16 v[76:79], v[180:183], v[24:27], v[76:79]
	v_mfma_f32_16x16x32_bf16 v[80:83], v[184:187], v[24:27], v[80:83]
	v_mfma_f32_16x16x32_bf16 v[88:91], v[188:191], v[24:27], v[88:91]
	s_waitcnt vmcnt(12)
	v_mfma_f32_16x16x32_bf16 v[84:87], v[192:195], v[28:31], v[84:87]
	v_mfma_f32_16x16x32_bf16 v[76:79], v[196:199], v[28:31], v[76:79]
	v_mfma_f32_16x16x32_bf16 v[80:83], v[200:203], v[28:31], v[80:83]
	v_mfma_f32_16x16x32_bf16 v[88:91], v[204:207], v[28:31], v[88:91]
	s_waitcnt vmcnt(8)
	v_mfma_f32_16x16x32_bf16 v[84:87], v[208:211], v[32:35], v[84:87]
	v_mfma_f32_16x16x32_bf16 v[76:79], v[212:215], v[32:35], v[76:79]
	v_mfma_f32_16x16x32_bf16 v[80:83], v[216:219], v[32:35], v[80:83]
	v_mfma_f32_16x16x32_bf16 v[88:91], v[220:223], v[32:35], v[88:91]
	s_waitcnt vmcnt(4)
	v_mfma_f32_16x16x32_bf16 v[84:87], v[224:227], v[36:39], v[84:87]
	v_mfma_f32_16x16x32_bf16 v[76:79], v[228:231], v[36:39], v[76:79]
	v_mfma_f32_16x16x32_bf16 v[80:83], v[232:235], v[36:39], v[80:83]
	v_mfma_f32_16x16x32_bf16 v[88:91], v[236:239], v[36:39], v[88:91]
	s_waitcnt vmcnt(0)
	v_mfma_f32_16x16x32_bf16 v[84:87], v[56:59], v[40:43], v[84:87]
	v_mfma_f32_16x16x32_bf16 v[76:79], v[44:47], v[40:43], v[76:79]
	v_mfma_f32_16x16x32_bf16 v[80:83], v[48:51], v[40:43], v[80:83]
	v_mfma_f32_16x16x32_bf16 v[88:91], v[68:71], v[40:43], v[88:91]
	s_add_i32 s15, s15, s73
	s_cmpk_gt_i32 s15, 0xff
	s_cselect_b64 s[4:5], -1, 0
	s_and_b64 vcc, exec, s[4:5]
	s_nop 7
	s_cbranch_vccnz .LBB0_675
	s_lshr_b32 s16, s15, 31
	s_add_i32 s16, s15, s16
	s_ashr_i32 s17, s16, 1
	s_lshl_b32 s16, s17, 4
	v_or_b32_e32 v2, s16, v102
	v_mov_b64_e32 v[0:1], s[8:9]
	v_mad_i64_i32 v[0:1], s[18:19], v2, s13, v[0:1]
	s_mulk_i32 s17, 0xea00
	s_add_i32 s18, s0, s17
	s_ashr_i32 s19, s18, 31
	s_lshl_b64 s[18:19], s[18:19], 1
	v_lshl_add_u64 v[94:95], v[96:97], 0, s[18:19]
	v_lshl_add_u64 v[0:1], v[0:1], 0, s[18:19]
	v_add_co_u32_e32 v106, vcc, s1, v94
	v_lshl_add_u64 v[48:49], v[92:93], 1, v[0:1]
	s_nop 0
	v_addc_co_u32_e32 v107, vcc, 0, v95, vcc
	global_load_dwordx4 v[0:3], v[48:49], off
	global_load_dwordx4 v[4:7], v[48:49], off offset:64
	global_load_dwordx4 v[8:11], v[48:49], off offset:128
	global_load_dwordx4 v[12:15], v[48:49], off offset:192
	global_load_dwordx4 v[16:19], v[48:49], off offset:256
	global_load_dwordx4 v[20:23], v[48:49], off offset:320
	global_load_dwordx4 v[24:27], v[48:49], off offset:384
	global_load_dwordx4 v[28:31], v[48:49], off offset:448
	global_load_dwordx4 v[32:35], v[48:49], off offset:512
	global_load_dwordx4 v[36:39], v[48:49], off offset:576
	v_add_co_u32_e32 v108, vcc, 0x58000, v94
	global_load_dwordx4 v[40:43], v[48:49], off offset:640
	global_load_dwordx4 v[44:47], v[106:107], off
	v_addc_co_u32_e32 v109, vcc, 0, v95, vcc
	v_add_co_u32_e32 v110, vcc, 0x84000, v94
	s_nop 1
	v_addc_co_u32_e32 v111, vcc, 0, v95, vcc
	global_load_dwordx4 v[60:63], v[94:95], off offset:64
	global_load_dwordx4 v[48:51], v[108:109], off
	global_load_dwordx4 v[52:55], v[106:107], off offset:64
	global_load_dwordx4 v[68:71], v[110:111], off
	global_load_dwordx4 v[72:75], v[108:109], off offset:64
	global_load_dwordx4 v[56:59], v[94:95], off
	global_load_dwordx4 v[64:67], v[110:111], off offset:64
	s_branch .LBB0_675

.LBB0_2477:
	v_add_co_u32_e32 v106, vcc, s1, v94
	s_nop 1
	v_addc_co_u32_e32 v107, vcc, 0, v95, vcc
	v_add_co_u32_e32 v108, vcc, s10, v94
	s_nop 1
	v_addc_co_u32_e32 v109, vcc, 0, v95, vcc
	v_add_co_u32_e32 v110, vcc, s11, v94
	s_nop 1
	v_addc_co_u32_e32 v111, vcc, 0, v95, vcc
	global_load_dwordx4 v[112:115], v[94:95], off offset:128
	global_load_dwordx4 v[116:119], v[106:107], off offset:128
	global_load_dwordx4 v[120:123], v[108:109], off offset:128
	global_load_dwordx4 v[124:127], v[110:111], off offset:128
	global_load_dwordx4 v[128:131], v[94:95], off offset:192
	global_load_dwordx4 v[132:135], v[106:107], off offset:192
	global_load_dwordx4 v[136:139], v[108:109], off offset:192
	global_load_dwordx4 v[140:143], v[110:111], off offset:192
	global_load_dwordx4 v[144:147], v[94:95], off offset:256
	global_load_dwordx4 v[148:151], v[106:107], off offset:256
	global_load_dwordx4 v[152:155], v[108:109], off offset:256
	global_load_dwordx4 v[156:159], v[110:111], off offset:256
	global_load_dwordx4 v[160:163], v[94:95], off offset:320
	global_load_dwordx4 v[164:167], v[106:107], off offset:320
	global_load_dwordx4 v[168:171], v[108:109], off offset:320
	global_load_dwordx4 v[172:175], v[110:111], off offset:320
	global_load_dwordx4 v[176:179], v[94:95], off offset:384
	global_load_dwordx4 v[180:183], v[106:107], off offset:384
	global_load_dwordx4 v[184:187], v[108:109], off offset:384
	global_load_dwordx4 v[188:191], v[110:111], off offset:384
	global_load_dwordx4 v[192:195], v[94:95], off offset:448
	global_load_dwordx4 v[196:199], v[106:107], off offset:448
	global_load_dwordx4 v[200:203], v[108:109], off offset:448
	global_load_dwordx4 v[204:207], v[110:111], off offset:448
	global_load_dwordx4 v[208:211], v[94:95], off offset:512
	global_load_dwordx4 v[212:215], v[106:107], off offset:512
	global_load_dwordx4 v[216:219], v[108:109], off offset:512
	global_load_dwordx4 v[220:223], v[110:111], off offset:512
	global_load_dwordx4 v[224:227], v[94:95], off offset:576
	global_load_dwordx4 v[228:231], v[106:107], off offset:576
	global_load_dwordx4 v[232:235], v[108:109], off offset:576
	global_load_dwordx4 v[236:239], v[110:111], off offset:576
	s_waitcnt vmcnt(32)
	v_mfma_f32_16x16x32_bf16 v[84:87], v[56:59], v[0:3], 0
	v_mfma_f32_16x16x32_bf16 v[76:79], v[44:47], v[0:3], 0
	v_mfma_f32_16x16x32_bf16 v[80:83], v[48:51], v[0:3], 0
	v_mfma_f32_16x16x32_bf16 v[88:91], v[68:71], v[0:3], 0
	v_mfma_f32_16x16x32_bf16 v[84:87], v[60:63], v[4:7], v[84:87]
	v_mfma_f32_16x16x32_bf16 v[76:79], v[52:55], v[4:7], v[76:79]
	v_mfma_f32_16x16x32_bf16 v[80:83], v[72:75], v[4:7], v[80:83]
	v_mfma_f32_16x16x32_bf16 v[88:91], v[64:67], v[4:7], v[88:91]
	global_load_dwordx4 v[56:59], v[94:95], off offset:640
	global_load_dwordx4 v[44:47], v[106:107], off offset:640
	global_load_dwordx4 v[48:51], v[108:109], off offset:640
	global_load_dwordx4 v[68:71], v[110:111], off offset:640
	s_waitcnt vmcnt(32)
	v_mfma_f32_16x16x32_bf16 v[84:87], v[112:115], v[8:11], v[84:87]
	v_mfma_f32_16x16x32_bf16 v[76:79], v[116:119], v[8:11], v[76:79]
	v_mfma_f32_16x16x32_bf16 v[80:83], v[120:123], v[8:11], v[80:83]
	v_mfma_f32_16x16x32_bf16 v[88:91], v[124:127], v[8:11], v[88:91]
	s_waitcnt vmcnt(28)
	v_mfma_f32_16x16x32_bf16 v[84:87], v[128:131], v[12:15], v[84:87]
	v_mfma_f32_16x16x32_bf16 v[76:79], v[132:135], v[12:15], v[76:79]
	v_mfma_f32_16x16x32_bf16 v[80:83], v[136:139], v[12:15], v[80:83]
	v_mfma_f32_16x16x32_bf16 v[88:91], v[140:143], v[12:15], v[88:91]
	s_waitcnt vmcnt(24)
	v_mfma_f32_16x16x32_bf16 v[84:87], v[144:147], v[16:19], v[84:87]
	v_mfma_f32_16x16x32_bf16 v[76:79], v[148:151], v[16:19], v[76:79]
	v_mfma_f32_16x16x32_bf16 v[80:83], v[152:155], v[16:19], v[80:83]
	v_mfma_f32_16x16x32_bf16 v[88:91], v[156:159], v[16:19], v[88:91]
	s_waitcnt vmcnt(20)
	v_mfma_f32_16x16x32_bf16 v[84:87], v[160:163], v[20:23], v[84:87]
	v_mfma_f32_16x16x32_bf16 v[76:79], v[164:167], v[20:23], v[76:79]
	v_mfma_f32_16x16x32_bf16 v[80:83], v[168:171], v[20:23], v[80:83]
	v_mfma_f32_16x16x32_bf16 v[88:91], v[172:175], v[20:23], v[88:91]
	s_waitcnt vmcnt(16)
	v_mfma_f32_16x16x32_bf16 v[84:87], v[176:179], v[24:27], v[84:87]
	v_mfma_f32_16x16x32_bf16 v[76:79], v[180:183], v[24:27], v[76:79]
	v_mfma_f32_16x16x32_bf16 v[80:83], v[184:187], v[24:27], v[80:83]
	v_mfma_f32_16x16x32_bf16 v[88:91], v[188:191], v[24:27], v[88:91]
	s_waitcnt vmcnt(12)
	v_mfma_f32_16x16x32_bf16 v[84:87], v[192:195], v[28:31], v[84:87]
	v_mfma_f32_16x16x32_bf16 v[76:79], v[196:199], v[28:31], v[76:79]
	v_mfma_f32_16x16x32_bf16 v[80:83], v[200:203], v[28:31], v[80:83]
	v_mfma_f32_16x16x32_bf16 v[88:91], v[204:207], v[28:31], v[88:91]
	s_waitcnt vmcnt(8)
	v_mfma_f32_16x16x32_bf16 v[84:87], v[208:211], v[32:35], v[84:87]
	v_mfma_f32_16x16x32_bf16 v[76:79], v[212:215], v[32:35], v[76:79]
	v_mfma_f32_16x16x32_bf16 v[80:83], v[216:219], v[32:35], v[80:83]
	v_mfma_f32_16x16x32_bf16 v[88:91], v[220:223], v[32:35], v[88:91]
	s_waitcnt vmcnt(4)
	v_mfma_f32_16x16x32_bf16 v[84:87], v[224:227], v[36:39], v[84:87]
	v_mfma_f32_16x16x32_bf16 v[76:79], v[228:231], v[36:39], v[76:79]
	v_mfma_f32_16x16x32_bf16 v[80:83], v[232:235], v[36:39], v[80:83]
	v_mfma_f32_16x16x32_bf16 v[88:91], v[236:239], v[36:39], v[88:91]
	s_waitcnt vmcnt(0)
	v_mfma_f32_16x16x32_bf16 v[84:87], v[56:59], v[40:43], v[84:87]
	v_mfma_f32_16x16x32_bf16 v[76:79], v[44:47], v[40:43], v[76:79]
	v_mfma_f32_16x16x32_bf16 v[80:83], v[48:51], v[40:43], v[80:83]
	v_mfma_f32_16x16x32_bf16 v[88:91], v[68:71], v[40:43], v[88:91]
	s_add_i32 s33, s33, s73
	s_cmpk_gt_i32 s33, 0xff
	s_cselect_b64 s[4:5], -1, 0
	s_and_b64 vcc, exec, s[4:5]
	s_nop 7
	s_cbranch_vccnz .LBB0_2476
	s_lshr_b32 s15, s33, 31
	s_add_i32 s15, s33, s15
	s_ashr_i32 s18, s15, 1
	s_lshl_b32 s15, s18, 4
	v_or_b32_e32 v2, s15, v102
	v_mov_b64_e32 v[0:1], s[8:9]
	v_mad_i64_i32 v[0:1], s[16:17], v2, s13, v[0:1]
	s_mulk_i32 s18, 0xea00
	s_add_i32 s16, s0, s18
	s_ashr_i32 s17, s16, 31
	s_lshl_b64 s[16:17], s[16:17], 1
	v_lshl_add_u64 v[94:95], v[96:97], 0, s[16:17]
	v_lshl_add_u64 v[0:1], v[0:1], 0, s[16:17]
	v_add_co_u32_e32 v106, vcc, s1, v94
	v_lshl_add_u64 v[48:49], v[92:93], 1, v[0:1]
	s_nop 0
	v_addc_co_u32_e32 v107, vcc, 0, v95, vcc
	global_load_dwordx4 v[0:3], v[48:49], off
	global_load_dwordx4 v[4:7], v[48:49], off offset:64
	global_load_dwordx4 v[8:11], v[48:49], off offset:128
	global_load_dwordx4 v[12:15], v[48:49], off offset:192
	global_load_dwordx4 v[16:19], v[48:49], off offset:256
	global_load_dwordx4 v[20:23], v[48:49], off offset:320
	global_load_dwordx4 v[24:27], v[48:49], off offset:384
	global_load_dwordx4 v[28:31], v[48:49], off offset:448
	global_load_dwordx4 v[32:35], v[48:49], off offset:512
	global_load_dwordx4 v[36:39], v[48:49], off offset:576
	v_add_co_u32_e32 v108, vcc, 0x58000, v94
	global_load_dwordx4 v[40:43], v[48:49], off offset:640
	global_load_dwordx4 v[44:47], v[106:107], off
	v_addc_co_u32_e32 v109, vcc, 0, v95, vcc
	v_add_co_u32_e32 v110, vcc, 0x84000, v94
	s_nop 1
	v_addc_co_u32_e32 v111, vcc, 0, v95, vcc
	global_load_dwordx4 v[60:63], v[94:95], off offset:64
	global_load_dwordx4 v[48:51], v[108:109], off
	global_load_dwordx4 v[52:55], v[106:107], off offset:64
	global_load_dwordx4 v[68:71], v[110:111], off
	global_load_dwordx4 v[72:75], v[108:109], off offset:64
	global_load_dwordx4 v[56:59], v[94:95], off
	global_load_dwordx4 v[64:67], v[110:111], off offset:64
	s_branch .LBB0_2476
